# rstd table in LDS per GEMM phase for IN/UP epilogue instead of 32 global loads per unit
# speedup vs baseline: 1.0130x; 1.0130x over previous
; #define PG8_BAR __builtin_amdgcn_s_barrier()
; #define PG8_STA(bufoff, gbase, ld) PG8_STAGE(bufoff, gbase, RA0 * (unsigned)(ld) + CC0, RA1 * (unsigned)(ld) + CC1)
; #define PG8_STB(bufoff, gbase, ld) PG8_STAGE(bufoff, gbase, RB0 * (unsigned)(ld) + CC0, RB1 * (unsigned)(ld) + CC1)
; __device__ __forceinline__ void epi_rstd(const float* ssq, int row0, int fq, float (&rs)[2][4]) {
;     ...
;             for (int j = 0; j < 4; ++j) part[ai][m][j] = ssq[(size_t)(4 * fq + j) * M + row0 + ai * 128 + m * 16];
; __device__ __forceinline__ void gemm_phase(LAS unsigned char* lds, const Sched& S, const Epi& E) {
;     ...
;     int R0, C0, R1, C1; stage_rc(tid * 16, R0, C0); stage_rc(tid * 16 + 8192, R1, C1);
;     const int Rb0 = (R0 & ~31) + perm32(R0 & 31), Rb1 = (R1 & ~31) + perm32(R1 & 31);
;     const size_t kstep = (size_t)(BK * 2);
;     const unsigned ldsw = (unsigned)wid * 1024u;
;     const int aoff = lds_byte(wr * 64 + fr, fq * 8), boff = lds_byte(wc * 32 + fr, fq * 8);
;     ...
;     Unit cur, nxt; int ui = 0;
;     if (!S.next(0, cur)) return;
;     f32x4 acc[2][2][4][2];
; #pragma unroll
;     for (int a = 0; a < 2; ++a)
; #pragma unroll
;         for (int b = 0; b < 2; ++b)
; #pragma unroll
;             for (int m = 0; m < 4; ++m)
; #pragma unroll
;                 for (int n = 0; n < 2; ++n) acc[a][b][m][n] = (f32x4){0.f, 0.f, 0.f, 0.f};
;     bf16x8 At[4][2], B0[2][2], B1[2][2];
;     const char* cA = cur.a; const char* cB = cur.b;
;     const unsigned RA0 = R0 * 2, RA1 = R1 * 2, RB0 = Rb0 * 2, RB1 = Rb1 * 2, CC0 = C0 * 2, CC1 = C1 * 2;
;     ...
;     int lda = cur.lda, ldb = cur.ldb;
;     { const size_t hA = (size_t)HALF * lda * 2, hB = (size_t)HALF * ldb * 2;
;     PG8_STB(PG8_SB(0, 0), cB, ldb); PG8_STB(PG8_SB(0, 1), cB + hB, ldb); PG8_STA(PG8_SA(0, 0), cA, lda); PG8_STA(PG8_SA(0, 1), cA + hA, lda);
;     if (wr == 1) PG8_BAR;
.LBB0_253:
	s_andn2_b64 vcc, exec, s[6:7]
	s_cbranch_vccnz .LBB0_355
	v_readlane_b32 s12, v250, 3
	v_readlane_b32 s13, v250, 4
	v_and_b32_e32 v64, 0xff, v195
	v_lshl_add_u32 v64, s95, 8, v64
	v_lshlrev_b32_e32 v64, 2, v64
	s_nop 3
	global_load_dword v66, v64, s[12:13]
	v_add_u32_e32 v65, 0x10000, v64
	global_load_dword v67, v65, s[12:13]
	v_add_u32_e32 v65, 0x20000, v64
	global_load_dword v68, v65, s[12:13]
	v_add_u32_e32 v65, 0x30000, v64
	global_load_dword v69, v65, s[12:13]
	v_add_u32_e32 v65, 0x40000, v64
	global_load_dword v70, v65, s[12:13]
	v_add_u32_e32 v65, 0x50000, v64
	global_load_dword v71, v65, s[12:13]
	v_add_u32_e32 v65, 0x60000, v64
	global_load_dword v72, v65, s[12:13]
	v_add_u32_e32 v65, 0x70000, v64
	global_load_dword v73, v65, s[12:13]
	v_add_u32_e32 v65, 0x80000, v64
	global_load_dword v74, v65, s[12:13]
	v_add_u32_e32 v65, 0x90000, v64
	global_load_dword v75, v65, s[12:13]
	v_add_u32_e32 v65, 0xa0000, v64
	global_load_dword v76, v65, s[12:13]
	v_add_u32_e32 v65, 0xb0000, v64
	global_load_dword v77, v65, s[12:13]
	v_add_u32_e32 v65, 0xc0000, v64
	global_load_dword v78, v65, s[12:13]
	v_add_u32_e32 v65, 0xd0000, v64
	global_load_dword v79, v65, s[12:13]
	v_add_u32_e32 v65, 0xe0000, v64
	global_load_dword v80, v65, s[12:13]
	v_add_u32_e32 v65, 0xf0000, v64
	global_load_dword v81, v65, s[12:13]
	v_bfe_i32 v3, v17, 27, 1
	v_lshlrev_b32_e32 v2, 4, v17
	v_lshrrev_b32_e32 v3, 22, v3
	v_add_u32_e32 v3, v2, v3
	v_and_b32_e32 v3, 0xfffffc00, v3
	v_sub_u32_e32 v3, v2, v3
	v_lshrrev_b32_e32 v4, 4, v3
	v_bitop3_b32 v3, v4, v3, 32 bitop3:0x6c
	v_ashrrev_i32_e32 v5, 31, v3
	v_lshrrev_b32_e32 v5, 26, v5
	v_add_u32_e32 v5, v3, v5
	v_ashrrev_i32_e32 v6, 6, v5
	v_and_b32_e32 v5, 0xc0, v5
	v_sub_u32_e32 v3, v3, v5
	v_ashrrev_i16_sdwa v3, v199, sext(v3) dst_sel:DWORD dst_unused:UNUSED_PAD src0_sel:DWORD src1_sel:BYTE_0
	v_add_u32_e32 v2, 0x2000, v2
	v_bfe_i32 v14, v3, 0, 16
	v_ashrrev_i32_e32 v3, 31, v2
	v_lshrrev_b32_e32 v3, 22, v3
	v_add_u32_e32 v3, v2, v3
	v_ashrrev_i32_e32 v15, 10, v3
	v_mul_i32_i24_e32 v3, 0x400, v15
	v_sub_u32_e32 v2, v2, v3
	v_ashrrev_i32_e32 v0, 31, v17
	v_lshrrev_b32_e32 v3, 4, v2
	v_lshrrev_b32_e32 v0, 26, v0
	v_bitop3_b32 v2, v3, v2, 32 bitop3:0x6c
	v_add_u32_e32 v0, v17, v0
	v_ashrrev_i32_e32 v5, 31, v2
	v_ashrrev_i32_e32 v0, 6, v0
	v_lshrrev_b32_e32 v5, 26, v5
	v_lshlrev_b32_e32 v4, 3, v0
	v_add_u32_e32 v5, v2, v5
	v_and_b32_e32 v4, -16, v4
	v_ashrrev_i32_e32 v8, 6, v5
	v_and_b32_e32 v5, 0xc0, v5
	v_add_u32_e32 v4, v6, v4
	v_lshlrev_b32_e32 v3, 3, v15
	v_sub_u32_e32 v2, v2, v5
	v_and_b32_e32 v3, -16, v3
	v_ashrrev_i16_sdwa v2, v199, sext(v2) dst_sel:DWORD dst_unused:UNUSED_PAD src0_sel:DWORD src1_sel:BYTE_0
	v_lshlrev_b32_e32 v235, 1, v4
	v_lshrrev_b32_e32 v5, 2, v4
	v_and_b32_e32 v6, 3, v6
	s_mov_b32 s11, 0x7fffffe0
	v_add_u32_e32 v3, v8, v3
	v_bfe_i32 v16, v2, 0, 16
	v_and_b32_e32 v2, 24, v235
	v_and_b32_e32 v5, 4, v5
	v_and_or_b32 v4, v4, s11, v6
	s_ashr_i32 s7, s2, 6
	v_lshlrev_b32_e32 v7, 5, v0
	v_or3_b32 v2, v4, v5, v2
	v_lshlrev_b32_e32 v236, 1, v3
	v_lshrrev_b32_e32 v5, 2, v3
	v_and_b32_e32 v6, 3, v8
	v_and_b32_e32 v7, 32, v7
	v_lshlrev_b32_e32 v9, 5, v15
	v_and_b32_e32 v4, 24, v236
	v_and_b32_e32 v5, 4, v5
	v_and_or_b32 v3, v3, s11, v6
	s_lshl_b32 s25, s7, 10
	v_and_b32_e32 v9, 32, v9
	v_or3_b32 v3, v3, v5, v4
	v_lshlrev_b32_e32 v237, 1, v2
	v_add_lshl_u32 v194, v7, v14, 1
	v_readlane_b32 s21, v250, 20
	s_add_i32 s34, s25, 0
	v_lshlrev_b32_e32 v238, 1, v3
	v_add_lshl_u32 v196, v9, v16, 1
	v_readlane_b32 s20, v250, 12
	v_mad_u64_u32 v[8:9], s[12:13], v237, s21, v[194:195]
	s_add_i32 m0, s34, 0x10000
	s_ashr_i32 s6, s2, 8
	s_lshl_b32 s11, s20, 8
	s_lshl_b32 s17, s21, 8
	global_load_lds_dwordx4 v8, s[8:9]
	v_mad_u64_u32 v[10:11], s[12:13], v238, s21, v[196:197]
	s_add_i32 m0, s34, 0x12000
	s_add_u32 s12, s8, s17
	global_load_lds_dwordx4 v10, s[8:9]
	s_addc_u32 s13, s9, 0
	s_add_i32 m0, s34, 0x14000
	v_mov_b32_e32 v9, v1
	v_mov_b32_e32 v11, v1
	global_load_lds_dwordx4 v8, s[12:13]
	s_add_i32 m0, s34, 0x16000
	v_lshl_add_u64 v[2:3], s[8:9], 0, v[8:9]
	v_lshl_add_u64 v[6:7], s[12:13], 0, v[8:9]
	v_lshl_add_u64 v[8:9], s[12:13], 0, v[10:11]
	global_load_lds_dwordx4 v10, s[12:13]
	v_mad_u64_u32 v[18:19], s[12:13], v235, s20, v[194:195]
	v_mad_u64_u32 v[20:21], s[12:13], v236, s20, v[196:197]
	s_add_i32 s35, s34, 0x2000
	s_mov_b32 m0, s34
	s_add_u32 s12, s96, s11
	global_load_lds_dwordx4 v18, s[96:97]
	s_mov_b32 m0, s35
	s_addc_u32 s13, s97, 0
	s_add_i32 s39, s34, 0x4000
	global_load_lds_dwordx4 v20, s[96:97]
	s_mov_b32 m0, s39
	s_add_i32 s91, s34, 0x6000
	global_load_lds_dwordx4 v18, s[12:13]
	s_mov_b32 m0, s91
	s_cmp_eq_u32 s6, 1
	global_load_lds_dwordx4 v20, s[12:13]
	v_mov_b32_e32 v19, v1
	v_mov_b32_e32 v21, v1
	s_cselect_b64 s[12:13], -1, 0
	v_lshl_add_u64 v[4:5], s[8:9], 0, v[10:11]
	v_lshl_add_u64 v[10:11], s[96:97], 0, v[18:19]
	v_lshl_add_u64 v[12:13], s[96:97], 0, v[20:21]
	v_writelane_b32 v250, s12, 25
	s_cmp_lg_u32 s6, 1
	s_nop 0
	v_writelane_b32 v250, s13, 26
	s_cbranch_scc1 .LBB0_256
	s_barrier
; #define PG8_WAIT_V(n) asm volatile("s_waitcnt vmcnt(" #n ")" ::: "memory")
; #define PG8_BAR __builtin_amdgcn_s_barrier()
; #define PG8_STA(bufoff, gbase, ld) PG8_STAGE(bufoff, gbase, RA0 * (unsigned)(ld) + CC0, RA1 * (unsigned)(ld) + CC1)
; #define PG8_STB(bufoff, gbase, ld) PG8_STAGE(bufoff, gbase, RB0 * (unsigned)(ld) + CC0, RB1 * (unsigned)(ld) + CC1)
; __device__ __forceinline__ void epi_rstd(const float* ssq, int row0, int fq, float (&rs)[2][4]) {
;     ...
;         for (int m = 0; m < 4; ++m) { float t = (part[ai][m][0] + part[ai][m][1]) + (part[ai][m][2] + part[ai][m][3]); t += __shfl_xor(t, 16); t += __shfl_xor(t, 32); rs[ai][m] = __builtin_amdgcn_rsqf(t * (1.0f / 1024.0f) + EPS); }
; __device__ __forceinline__ void gemm_phase(LAS unsigned char* lds, const Sched& S, const Epi& E) {
;     ...
;     PG8_WAIT_V(2); PG8_BAR;
;     PG8_STB(PG8_SB(1, 0), cB + kstep, ldb); PG8_STA(PG8_SA(1, 0), cA + kstep, lda); PG8_STB(PG8_SB(1, 1), cB + hB + kstep, ldb);
;     PG8_WAIT_V(6); PG8_BAR; }
;     for (;;) {
;         const bool has_next = S.next(ui + 1, nxt);
;         const char* nA = has_next ? nxt.a : cA; const char* nB = has_next ? nxt.b : cB;
;         const int nlda = has_next ? nxt.lda : lda, nldb = has_next ? nxt.ldb : ldb;
;         const size_t hA = (size_t)HALF * lda * 2;
;         const int nt = cur.nt;
;         const int nt_main = has_next ? nt : nt - 2;
.LBB0_256:
	v_bfe_u32 v19, v17, 4, 2
	v_and_b32_e32 v18, 15, v17
	v_lshlrev_b32_e32 v21, 4, v19
	v_lshlrev_b32_e32 v17, 2, v17
	s_and_b32 s11, s7, 3
	v_lshl_or_b32 v239, s6, 6, v18
	v_lshl_or_b32 v18, v18, 6, v21
	s_lshl_b32 s6, s6, 13
	v_and_b32_e32 v17, 32, v17
	v_bitop3_b32 v240, v18, s6, v17 bitop3:0xde
	s_lshl_b32 s6, s11, 12
	v_bitop3_b32 v241, v18, s6, v17 bitop3:0xde
	v_readlane_b32 s6, v250, 7
	v_readlane_b32 s7, v250, 8
	s_lshl_b64 s[6:7], s[6:7], 2
	s_waitcnt lgkmcnt(0)
	s_add_u32 s4, s4, s6
	s_addc_u32 s5, s5, s7
	s_add_u32 s62, s70, 0x800000
	s_addc_u32 s63, s71, 0
	v_lshl_add_u64 v[2:3], v[2:3], 0, s[52:53]
	s_add_i32 m0, s34, 0x18000
	s_waitcnt vmcnt(2)
	s_barrier
	global_load_lds_dwordx4 v[2:3], off
	v_lshl_add_u64 v[2:3], v[4:5], 0, s[52:53]
	s_add_i32 m0, s34, 0x1a000
	s_add_i32 s90, s34, 0x8000
	global_load_lds_dwordx4 v[2:3], off
	v_lshl_add_u64 v[2:3], v[10:11], 0, s[52:53]
	s_mov_b32 m0, s90
	s_add_i32 s73, s34, 0xa000
	global_load_lds_dwordx4 v[2:3], off
	v_lshl_add_u64 v[2:3], v[12:13], 0, s[52:53]
	s_mov_b32 m0, s73
	v_writelane_b32 v250, s4, 27
	global_load_lds_dwordx4 v[2:3], off
	v_lshl_add_u64 v[2:3], v[6:7], 0, s[52:53]
	s_add_i32 m0, s34, 0x1c000
	v_writelane_b32 v250, s5, 28
	global_load_lds_dwordx4 v[2:3], off
	v_lshl_add_u64 v[2:3], v[8:9], 0, s[52:53]
	s_add_i32 m0, s34, 0x1e000
	s_cmpk_lt_u32 s2, 0x100
	global_load_lds_dwordx4 v[2:3], off
	s_cselect_b64 s[4:5], -1, 0
	s_lshl_b32 s6, s11, 14
	v_writelane_b32 v250, s11, 29
	s_or_b32 s6, s6, 0xfff80000
	v_writelane_b32 v250, s6, 30
	s_lshl_b32 s82, s15, 3
	v_readlane_b32 s6, v250, 21
	v_readlane_b32 s7, v250, 22
	v_readlane_b32 s61, v250, 20
	s_waitcnt vmcnt(6)
	v_add_f32_e32 v66, v66, v67
	v_add_f32_e32 v68, v68, v69
	v_add_f32_e32 v66, v66, v68
	v_add_f32_e32 v70, v70, v71
	v_add_f32_e32 v72, v72, v73
	v_add_f32_e32 v70, v70, v72
	v_add_f32_e32 v74, v74, v75
	v_add_f32_e32 v76, v76, v77
	v_add_f32_e32 v74, v74, v76
	v_add_f32_e32 v78, v78, v79
	v_add_f32_e32 v80, v80, v81
	v_add_f32_e32 v78, v78, v80
	v_add_f32_e32 v66, v66, v70
	v_add_f32_e32 v74, v74, v78
	v_add_f32_e32 v66, v66, v74
	v_fmamk_f32 v66, v66, 0x3a800000, v197
	v_rsq_f32_e32 v66, v66
	v_and_b32_e32 v65, 0xff, v195
	v_lshlrev_b32_e32 v65, 2, v65
	v_add_u32_e32 v65, 0x20800, v65
	ds_write_b32 v65, v66
	v_writelane_b32 v250, s95, 41
	v_and_b32_e32 v0, 1, v0
	v_cndmask_b32_e64 v2, 0, 1, s[6:7]
	s_lshr_b32 s6, s61, 6
	v_readfirstlane_b32 s36, v2
	v_cvt_f32_u32_e32 v2, s82
	v_writelane_b32 v250, s6, 31
	s_sub_i32 s6, 0, s82
	v_lshlrev_b32_e32 v20, 3, v19
	v_rcp_iflag_f32_e32 v2, v2
	v_lshlrev_b32_e32 v198, 16, v19
	v_lshl_or_b32 v242, s11, 5, v20
	s_mov_b32 s2, 0
	v_mul_f32_e32 v2, 0x4f7ffffe, v2
	v_cvt_u32_f32_e32 v2, v2
	v_cmp_eq_u32_e64 s[40:41], 0, v19
	v_or_b32_e32 v200, 0x4000, v198
	v_or_b32_e32 v202, 0x8000, v198
	v_readfirstlane_b32 s7, v2
	s_mul_i32 s6, s6, s7
	s_mul_hi_u32 s6, s7, s6
	s_add_i32 s6, s7, s6
	v_writelane_b32 v250, s6, 32
	v_lshlrev_b32_e32 v2, 1, v14
	v_lshl_add_u32 v206, v0, 6, v2
	v_and_b32_e32 v0, 1, v15
	v_lshlrev_b32_e32 v2, 1, v16
	v_readlane_b32 s6, v250, 12
	v_or_b32_e32 v204, 0xc000, v198
	s_mov_b32 s17, s31
	v_lshl_add_u32 v208, v0, 6, v2
	v_readlane_b32 s83, v250, 13
	s_mov_b32 s20, s6
	s_mov_b32 s11, s61
	s_mov_b64 s[12:13], s[8:9]
	s_mov_b64 s[6:7], s[96:97]
	s_waitcnt lgkmcnt(0)
	s_barrier
	s_branch .LBB0_259

; __device__ __forceinline__ void epi_rstd(const float* ssq, int row0, int fq, float (&rs)[2][4]) {
;     float part[2][4][4];
; #pragma unroll
;     for (int ai = 0; ai < 2; ++ai)
; #pragma unroll
;         for (int m = 0; m < 4; ++m)
; #pragma unroll
;             for (int j = 0; j < 4; ++j) part[ai][m][j] = ssq[(size_t)(4 * fq + j) * M + row0 + ai * 128 + m * 16];
; #pragma unroll
;     for (int ai = 0; ai < 2; ++ai)
; #pragma unroll
;         for (int m = 0; m < 4; ++m) { float t = (part[ai][m][0] + part[ai][m][1]) + (part[ai][m][2] + part[ai][m][3]); t += __shfl_xor(t, 16); t += __shfl_xor(t, 32); rs[ai][m] = __builtin_amdgcn_rsqf(t * (1.0f / 1024.0f) + EPS); }
; __device__ __forceinline__ void epi_run(const Epi& E, f32x4 (&acc)[2][2][4][2], const Unit& u, int wr, int wc, int fr, int fq) {
;     ...
;     if (mode == MODE_IN || mode == MODE_UP) {
;         float rs[2][4]; epi_rstd(E.ssq_in, row0, fq, rs);
.LBB0_326:
	s_and_b64 vcc, exec, s[44:45]
	s_cbranch_vccz .LBB0_351
	v_readlane_b32 s8, v250, 41
	s_nop 0
	s_cmp_lg_u32 s8, s95
	s_cbranch_scc1 .Lmy_rstd_slow
	v_ashrrev_i32_e32 v211, 31, v210
	v_cmp_lt_i32_e32 vcc, v233, v203
	v_lshlrev_b32_e32 v135, 2, v239
	v_add_u32_e32 v135, 0x20800, v135
	v_cndmask_b32_e32 v0, v201, v233, vcc
	v_cmp_lt_i32_e32 vcc, v234, v203
	v_lshlrev_b32_e32 v133, 2, v0
	s_nop 0
	v_cndmask_b32_e32 v0, v201, v234, vcc
	v_lshlrev_b32_e32 v131, 2, v0
	ds_read_b32 v130, v135
	ds_read_b32 v0, v135 offset:64
	ds_read_b32 v132, v135 offset:128
	ds_read_b32 v142, v135 offset:192
	ds_read_b32 v140, v135 offset:512
	ds_read_b32 v138, v135 offset:576
	ds_read_b32 v134, v135 offset:640
	ds_read_b32 v136, v135 offset:704
	s_mov_b64 s[8:9], -1
	s_waitcnt lgkmcnt(0)
	s_cmp_lg_u32 s83, 5
	s_branch .Lmy_rstd_join
.Lmy_rstd_slow:
	v_readlane_b32 s8, v250, 3
	v_ashrrev_i32_e32 v211, 31, v210
	v_readlane_b32 s9, v250, 4
	v_lshlrev_b32_e32 v0, 2, v198
	v_cmp_lt_i32_e32 vcc, v233, v203
	s_waitcnt lgkmcnt(0)
	v_lshl_add_u64 v[130:131], v[210:211], 2, s[8:9]
	v_lshl_add_u64 v[132:133], v[130:131], 0, v[0:1]
	v_lshlrev_b32_e32 v0, 2, v200
	v_lshl_add_u64 v[134:135], v[130:131], 0, v[0:1]
	global_load_dword v143, v[134:135], off
	v_lshlrev_b32_e32 v134, 2, v202
	v_mov_b32_e32 v135, v1
	v_lshl_add_u64 v[136:137], v[130:131], 0, v[134:135]
	global_load_dword v144, v[136:137], off
	v_lshlrev_b32_e32 v136, 2, v204
	v_mov_b32_e32 v137, v1
	v_lshl_add_u64 v[138:139], v[130:131], 0, v[136:137]
	global_load_dword v142, v[132:133], off
	global_load_dword v146, v[132:133], off offset:64
	global_load_dword v150, v[132:133], off offset:128
	global_load_dword v154, v[132:133], off offset:192
	global_load_dword v158, v[132:133], off offset:512
	global_load_dword v162, v[132:133], off offset:576
	global_load_dword v166, v[132:133], off offset:640
	global_load_dword v168, v[132:133], off offset:704
	global_load_dword v145, v[138:139], off
	v_lshl_add_u64 v[138:139], v[130:131], 0, 64
	v_lshl_add_u64 v[140:141], v[138:139], 0, v[0:1]
	global_load_dword v147, v[140:141], off
	v_lshl_add_u64 v[140:141], v[138:139], 0, v[134:135]
	v_lshl_add_u64 v[138:139], v[138:139], 0, v[136:137]
	global_load_dword v148, v[140:141], off
	global_load_dword v149, v[138:139], off
	v_lshl_add_u64 v[138:139], v[130:131], 0, s[52:53]
	v_lshl_add_u64 v[140:141], v[138:139], 0, v[0:1]
	global_load_dword v151, v[140:141], off
	v_lshl_add_u64 v[140:141], v[138:139], 0, v[134:135]
	v_lshl_add_u64 v[138:139], v[138:139], 0, v[136:137]
	global_load_dword v152, v[140:141], off
	global_load_dword v153, v[138:139], off
	s_mov_b64 s[8:9], 0xc0
	v_lshl_add_u64 v[138:139], v[130:131], 0, s[8:9]
	v_lshl_add_u64 v[140:141], v[138:139], 0, v[0:1]
	global_load_dword v155, v[140:141], off
	v_lshl_add_u64 v[140:141], v[138:139], 0, v[134:135]
	v_lshl_add_u64 v[138:139], v[138:139], 0, v[136:137]
	global_load_dword v156, v[140:141], off
	global_load_dword v157, v[138:139], off
	s_mov_b64 s[8:9], 0x200
	v_lshl_add_u64 v[138:139], v[130:131], 0, s[8:9]
	v_lshl_add_u64 v[140:141], v[138:139], 0, v[0:1]
	global_load_dword v159, v[140:141], off
	v_lshl_add_u64 v[140:141], v[138:139], 0, v[134:135]
	v_lshl_add_u64 v[138:139], v[138:139], 0, v[136:137]
	global_load_dword v160, v[140:141], off
	global_load_dword v161, v[138:139], off
	s_mov_b64 s[8:9], 0x240
	v_lshl_add_u64 v[138:139], v[130:131], 0, s[8:9]
	v_lshl_add_u64 v[140:141], v[138:139], 0, v[0:1]
	global_load_dword v163, v[140:141], off
	v_lshl_add_u64 v[140:141], v[138:139], 0, v[134:135]
	v_lshl_add_u64 v[138:139], v[138:139], 0, v[136:137]
	global_load_dword v164, v[140:141], off
	global_load_dword v165, v[138:139], off
	s_mov_b64 s[8:9], 0x280
	v_lshl_add_u64 v[138:139], v[130:131], 0, s[8:9]
	s_mov_b64 s[8:9], 0x2c0
	v_lshl_add_u64 v[140:141], v[138:139], 0, v[0:1]
	v_lshl_add_u64 v[130:131], v[130:131], 0, s[8:9]
	global_load_dword v167, v[140:141], off
	v_lshl_add_u64 v[140:141], v[138:139], 0, v[134:135]
	v_lshl_add_u64 v[138:139], v[138:139], 0, v[136:137]
	v_lshl_add_u64 v[132:133], v[130:131], 0, v[0:1]
	global_load_dword v139, v[138:139], off
	v_cndmask_b32_e32 v0, v201, v233, vcc
	global_load_dword v169, v[132:133], off
	v_lshl_add_u64 v[132:133], v[130:131], 0, v[134:135]
	v_lshl_add_u64 v[130:131], v[130:131], 0, v[136:137]
	v_cmp_lt_i32_e32 vcc, v234, v203
	global_load_dword v141, v[140:141], off
	s_cmp_lg_u32 s83, 5
	global_load_dword v135, v[132:133], off
	global_load_dword v136, v[130:131], off
	v_lshlrev_b32_e32 v133, 2, v0
	v_cndmask_b32_e32 v0, v201, v234, vcc
	v_lshlrev_b32_e32 v131, 2, v0
	s_mov_b64 s[8:9], -1
	s_waitcnt vmcnt(0)
	v_add_f32_e32 v0, v142, v143
	v_add_f32_e32 v130, v144, v145
	v_add_f32_e32 v0, v0, v130
	ds_bpermute_b32 v130, v133, v0
	s_waitcnt lgkmcnt(0)
	v_add_f32_e32 v0, v0, v130
	ds_bpermute_b32 v130, v131, v0
	v_add_f32_e32 v132, v148, v149
	s_waitcnt lgkmcnt(0)
	v_add_f32_e32 v0, v0, v130
	v_fmamk_f32 v0, v0, 0x3a800000, v197
	v_rsq_f32_e32 v130, v0
	v_add_f32_e32 v0, v146, v147
	v_add_f32_e32 v0, v0, v132
	ds_bpermute_b32 v132, v133, v0
	v_add_f32_e32 v134, v152, v153
	v_add_f32_e32 v137, v156, v157
	s_waitcnt lgkmcnt(0)
	v_add_f32_e32 v0, v0, v132
	ds_bpermute_b32 v132, v131, v0
	s_waitcnt lgkmcnt(0)
	v_add_f32_e32 v0, v0, v132
	v_add_f32_e32 v132, v150, v151
	v_add_f32_e32 v132, v132, v134
	ds_bpermute_b32 v134, v133, v132
	v_fmamk_f32 v0, v0, 0x3a800000, v197
	v_rsq_f32_e32 v0, v0
	s_waitcnt lgkmcnt(0)
	v_add_f32_e32 v132, v132, v134
	ds_bpermute_b32 v134, v131, v132
	s_waitcnt lgkmcnt(0)
; __device__ __forceinline__ float sigm(float v) { return __builtin_amdgcn_rcpf(1.0f + __builtin_amdgcn_exp2f(-1.44269504089f * v)); }
; __device__ __forceinline__ void epi_rstd(const float* ssq, int row0, int fq, float (&rs)[2][4]) {
;     ...
;         for (int m = 0; m < 4; ++m) { float t = (part[ai][m][0] + part[ai][m][1]) + (part[ai][m][2] + part[ai][m][3]); t += __shfl_xor(t, 16); t += __shfl_xor(t, 32); rs[ai][m] = __builtin_amdgcn_rsqf(t * (1.0f / 1024.0f) + EPS); }
; }
; template <int ACT> __device__ __forceinline__ void epi_act_store(f32x4 (&acc)[2][2][4][2], const float (&rs)[2][4], bf16_t* out, int ld, int row0, int col0, float* ssqv_slot, bool want_ssq, int fq) {
; #pragma unroll
;     for (int ai = 0; ai < 2; ++ai)
; #pragma unroll
;         for (int m = 0; m < 4; ++m) { const int row = row0 + ai * 128 + m * 16; float sq = 0.f;
; #pragma unroll
;             for (int bj = 0; bj < 2; ++bj) { f32x4 v0 = acc[ai][bj][m][0] * rs[ai][m], v1 = acc[ai][bj][m][1] * rs[ai][m];
;                 if (ACT == 1) { f32x2 a = gelu_pk((f32x2){v0[0], v0[1]}), b = gelu_pk((f32x2){v0[2], v0[3]}), c = gelu_pk((f32x2){v1[0], v1[1]}), d = gelu_pk((f32x2){v1[2], v1[3]});
;                     v0 = (f32x4){a.x, a.y, b.x, b.y}; v1 = (f32x4){c.x, c.y, d.x, d.y}; sq += sumsq8(v0, v1); }
;                 if (ACT == 2) {
; #pragma unroll
;                     for (int e = 0; e < 4; ++e) { v0[e] = sigm(v0[e]); v1[e] = sigm(v1[e]); } }
;                 *(u32x4*)(out + (size_t)row * ld + col0 + bj * 128) = pack8(v0, v1); }
;             if (ACT == 1) { if (want_ssq) { sq += __shfl_xor(sq, 16); sq += __shfl_xor(sq, 32); if (fq == 0) ssqv_slot[row] = sq; } } }
; }
; __device__ __forceinline__ void epi_run(const Epi& E, f32x4 (&acc)[2][2][4][2], const Unit& u, int wr, int wc, int fr, int fq) {
;     const int mode = u.mode;
;     const int row0 = u.pm * 256 + wr * 64 + fr, col0 = u.pn * 256 + wc * 32 + 8 * fq;
;     if (mode == MODE_IN || mode == MODE_UP) {
;         float rs[2][4]; epi_rstd(E.ssq_in, row0, fq, rs);
;         if (mode == MODE_UP) { epi_act_store<0>(acc, rs, E.out16, E.ld16, row0, col0, nullptr, false, fq); return; }
;         const int atype = u.pn >> 2;
;         if (atype == 2) epi_act_store<1>(acc, rs, E.Z, NIN, row0, col0, E.ssqv + (size_t)((u.pn - 8) * 4 + wc) * M, true, fq);
;         else epi_act_store<0>(acc, rs, E.Z, NIN, row0, col0, nullptr, false, fq);
	v_add_f32_e32 v132, v132, v134
	v_add_f32_e32 v134, v154, v155
	v_add_f32_e32 v134, v134, v137
	ds_bpermute_b32 v137, v133, v134
	v_fmamk_f32 v132, v132, 0x3a800000, v197
	v_rsq_f32_e32 v132, v132
	s_waitcnt lgkmcnt(0)
	v_add_f32_e32 v134, v134, v137
	ds_bpermute_b32 v137, v131, v134
	s_waitcnt lgkmcnt(0)
	v_add_f32_e32 v134, v134, v137
	v_fmamk_f32 v134, v134, 0x3a800000, v197
	v_rsq_f32_e32 v142, v134
	v_add_f32_e32 v134, v158, v159
	v_add_f32_e32 v137, v160, v161
	v_add_f32_e32 v134, v134, v137
	ds_bpermute_b32 v137, v133, v134
	v_add_f32_e32 v135, v135, v136
	s_waitcnt lgkmcnt(0)
	v_add_f32_e32 v134, v134, v137
	ds_bpermute_b32 v137, v131, v134
	s_waitcnt lgkmcnt(0)
	v_add_f32_e32 v134, v134, v137
	v_fmamk_f32 v134, v134, 0x3a800000, v197
	v_rsq_f32_e32 v140, v134
	v_add_f32_e32 v134, v162, v163
	v_add_f32_e32 v137, v164, v165
	v_add_f32_e32 v134, v134, v137
	ds_bpermute_b32 v137, v133, v134
	s_waitcnt lgkmcnt(0)
	v_add_f32_e32 v134, v134, v137
	ds_bpermute_b32 v137, v131, v134
	s_waitcnt lgkmcnt(0)
	v_add_f32_e32 v134, v134, v137
	v_fmamk_f32 v134, v134, 0x3a800000, v197
	v_rsq_f32_e32 v138, v134
	v_add_f32_e32 v134, v166, v167
	v_add_f32_e32 v137, v141, v139
	v_add_f32_e32 v134, v134, v137
	ds_bpermute_b32 v137, v133, v134
	s_waitcnt lgkmcnt(0)
	v_add_f32_e32 v134, v134, v137
	ds_bpermute_b32 v137, v131, v134
	s_waitcnt lgkmcnt(0)
	v_add_f32_e32 v134, v134, v137
	v_add_f32_e32 v137, v168, v169
	v_add_f32_e32 v135, v137, v135
	ds_bpermute_b32 v136, v133, v135
	v_fmamk_f32 v134, v134, 0x3a800000, v197
	v_rsq_f32_e32 v134, v134
	s_waitcnt lgkmcnt(0)
	v_add_f32_e32 v135, v135, v136
	ds_bpermute_b32 v136, v131, v135
	s_waitcnt lgkmcnt(0)
	v_add_f32_e32 v135, v135, v136
	v_fmamk_f32 v135, v135, 0x3a800000, v197
	v_rsq_f32_e32 v136, v135
.Lmy_rstd_join:
	s_cbranch_scc0 .LBB0_349
	s_and_b32 s2, s23, -4
	s_cmp_lg_u32 s2, 8
	s_cbranch_scc0 .LBB0_330
	v_ashrrev_i32_e32 v213, 31, v212
	v_lshl_add_u64 v[144:145], v[212:213], 1, s[70:71]
	v_pk_mul_f32 v[148:149], v[128:129], v[130:131] op_sel_hi:[1,0]
	v_pk_mul_f32 v[146:147], v[126:127], v[130:131] op_sel_hi:[1,0]
	v_pk_mul_f32 v[152:153], v[124:125], v[130:131] op_sel_hi:[1,0]
	v_pk_mul_f32 v[154:155], v[122:123], v[130:131] op_sel_hi:[1,0]
	v_mad_i64_i32 v[150:151], s[8:9], v210, s69, v[144:145]
	v_cvt_pk_bf16_f32 v146, v146, v147
	v_cvt_pk_bf16_f32 v147, v148, v149
	v_cvt_pk_bf16_f32 v148, v154, v155
	v_cvt_pk_bf16_f32 v149, v152, v153
	global_store_dwordx4 v[150:151], v[146:149], off
	v_pk_mul_f32 v[152:153], v[116:117], v[130:131] op_sel_hi:[1,0]
	v_pk_mul_f32 v[154:155], v[114:115], v[130:131] op_sel_hi:[1,0]
	v_pk_mul_f32 v[148:149], v[120:121], v[130:131] op_sel_hi:[1,0]
	v_pk_mul_f32 v[146:147], v[118:119], v[130:131] op_sel_hi:[1,0]
	v_or_b32_e32 v135, 16, v210
	v_cvt_pk_bf16_f32 v146, v146, v147
	v_cvt_pk_bf16_f32 v147, v148, v149
	v_cvt_pk_bf16_f32 v148, v154, v155
	v_cvt_pk_bf16_f32 v149, v152, v153
	global_store_dwordx4 v[150:151], v[146:149], off offset:256
	v_pk_mul_f32 v[152:153], v[108:109], v[0:1] op_sel_hi:[1,0]
	v_pk_mul_f32 v[154:155], v[106:107], v[0:1] op_sel_hi:[1,0]
	v_pk_mul_f32 v[148:149], v[112:113], v[0:1] op_sel_hi:[1,0]
	v_pk_mul_f32 v[146:147], v[110:111], v[0:1] op_sel_hi:[1,0]
	v_mad_i64_i32 v[150:151], s[8:9], v135, s69, v[144:145]
	v_cvt_pk_bf16_f32 v146, v146, v147
	v_cvt_pk_bf16_f32 v147, v148, v149
	v_cvt_pk_bf16_f32 v148, v154, v155
	v_cvt_pk_bf16_f32 v149, v152, v153
	global_store_dwordx4 v[150:151], v[146:149], off
	v_pk_mul_f32 v[152:153], v[96:97], v[0:1] op_sel_hi:[1,0]
	v_pk_mul_f32 v[154:155], v[94:95], v[0:1] op_sel_hi:[1,0]
	v_pk_mul_f32 v[148:149], v[104:105], v[0:1] op_sel_hi:[1,0]
	v_pk_mul_f32 v[146:147], v[102:103], v[0:1] op_sel_hi:[1,0]
	v_or_b32_e32 v135, 32, v210
	v_cvt_pk_bf16_f32 v146, v146, v147
	v_cvt_pk_bf16_f32 v147, v148, v149
	v_cvt_pk_bf16_f32 v148, v154, v155
	v_cvt_pk_bf16_f32 v149, v152, v153
	global_store_dwordx4 v[150:151], v[146:149], off offset:256
	v_pk_mul_f32 v[152:153], v[92:93], v[132:133] op_sel_hi:[1,0]
	v_pk_mul_f32 v[154:155], v[90:91], v[132:133] op_sel_hi:[1,0]
	v_pk_mul_f32 v[148:149], v[100:101], v[132:133] op_sel_hi:[1,0]
	v_pk_mul_f32 v[146:147], v[98:99], v[132:133] op_sel_hi:[1,0]
	v_mad_i64_i32 v[150:151], s[8:9], v135, s69, v[144:145]
	v_cvt_pk_bf16_f32 v146, v146, v147
	v_cvt_pk_bf16_f32 v147, v148, v149
	v_cvt_pk_bf16_f32 v148, v154, v155
	v_cvt_pk_bf16_f32 v149, v152, v153
	global_store_dwordx4 v[150:151], v[146:149], off
	v_pk_mul_f32 v[152:153], v[80:81], v[132:133] op_sel_hi:[1,0]
	v_pk_mul_f32 v[154:155], v[78:79], v[132:133] op_sel_hi:[1,0]
	v_pk_mul_f32 v[148:149], v[88:89], v[132:133] op_sel_hi:[1,0]
	v_pk_mul_f32 v[146:147], v[86:87], v[132:133] op_sel_hi:[1,0]
	v_or_b32_e32 v135, 48, v210
	v_cvt_pk_bf16_f32 v146, v146, v147
	v_cvt_pk_bf16_f32 v147, v148, v149
	v_cvt_pk_bf16_f32 v148, v154, v155
	v_cvt_pk_bf16_f32 v149, v152, v153
	global_store_dwordx4 v[150:151], v[146:149], off offset:256
; __device__ __forceinline__ float sigm(float v) { return __builtin_amdgcn_rcpf(1.0f + __builtin_amdgcn_exp2f(-1.44269504089f * v)); }
; __device__ __forceinline__ u32x4 pack8(const f32x4& v0, const f32x4& v1) { u32x4 w; w.x = cvt_pk_bf16(v0[0], v0[1]); w.y = cvt_pk_bf16(v0[2], v0[3]); w.z = cvt_pk_bf16(v1[0], v1[1]); w.w = cvt_pk_bf16(v1[2], v1[3]); return w; }
; __device__ __forceinline__ float sumsq8(const f32x4& v0, const f32x4& v1) { return (v0[0] * v0[0] + v0[1] * v0[1]) + (v0[2] * v0[2] + v0[3] * v0[3]) + (v1[0] * v1[0] + v1[1] * v1[1]) + (v1[2] * v1[2] + v1[3] * v1[3]); }
; template <int ACT> __device__ __forceinline__ void epi_act_store(f32x4 (&acc)[2][2][4][2], const float (&rs)[2][4], bf16_t* out, int ld, int row0, int col0, float* ssqv_slot, bool want_ssq, int fq) {
;     ...
;         for (int m = 0; m < 4; ++m) { const int row = row0 + ai * 128 + m * 16; float sq = 0.f;
; #pragma unroll
;             for (int bj = 0; bj < 2; ++bj) { f32x4 v0 = acc[ai][bj][m][0] * rs[ai][m], v1 = acc[ai][bj][m][1] * rs[ai][m];
;                 if (ACT == 1) { f32x2 a = gelu_pk((f32x2){v0[0], v0[1]}), b = gelu_pk((f32x2){v0[2], v0[3]}), c = gelu_pk((f32x2){v1[0], v1[1]}), d = gelu_pk((f32x2){v1[2], v1[3]});
;                     v0 = (f32x4){a.x, a.y, b.x, b.y}; v1 = (f32x4){c.x, c.y, d.x, d.y}; sq += sumsq8(v0, v1); }
;                 if (ACT == 2) {
; #pragma unroll
;                     for (int e = 0; e < 4; ++e) { v0[e] = sigm(v0[e]); v1[e] = sigm(v1[e]); } }
;                 *(u32x4*)(out + (size_t)row * ld + col0 + bj * 128) = pack8(v0, v1); }
	v_pk_mul_f32 v[152:153], v[76:77], v[142:143] op_sel_hi:[1,0]
	v_pk_mul_f32 v[154:155], v[74:75], v[142:143] op_sel_hi:[1,0]
	v_pk_mul_f32 v[148:149], v[84:85], v[142:143] op_sel_hi:[1,0]
	v_pk_mul_f32 v[146:147], v[82:83], v[142:143] op_sel_hi:[1,0]
	v_mad_i64_i32 v[150:151], s[8:9], v135, s69, v[144:145]
	v_cvt_pk_bf16_f32 v146, v146, v147
	v_cvt_pk_bf16_f32 v147, v148, v149
	v_cvt_pk_bf16_f32 v148, v154, v155
	v_cvt_pk_bf16_f32 v149, v152, v153
	global_store_dwordx4 v[150:151], v[146:149], off
	v_pk_mul_f32 v[152:153], v[68:69], v[142:143] op_sel_hi:[1,0]
	v_pk_mul_f32 v[154:155], v[66:67], v[142:143] op_sel_hi:[1,0]
	v_pk_mul_f32 v[148:149], v[72:73], v[142:143] op_sel_hi:[1,0]
	v_pk_mul_f32 v[146:147], v[70:71], v[142:143] op_sel_hi:[1,0]
	v_add_u32_e32 v135, 0x80, v210
	v_cvt_pk_bf16_f32 v146, v146, v147
	v_cvt_pk_bf16_f32 v147, v148, v149
	v_cvt_pk_bf16_f32 v148, v154, v155
	v_cvt_pk_bf16_f32 v149, v152, v153
	global_store_dwordx4 v[150:151], v[146:149], off offset:256
	v_pk_mul_f32 v[152:153], v[60:61], v[140:141] op_sel_hi:[1,0]
	v_pk_mul_f32 v[154:155], v[58:59], v[140:141] op_sel_hi:[1,0]
	v_pk_mul_f32 v[148:149], v[64:65], v[140:141] op_sel_hi:[1,0]
	v_pk_mul_f32 v[146:147], v[62:63], v[140:141] op_sel_hi:[1,0]
	v_mad_i64_i32 v[150:151], s[8:9], v135, s69, v[144:145]
	v_cvt_pk_bf16_f32 v146, v146, v147
	v_cvt_pk_bf16_f32 v147, v148, v149
	v_cvt_pk_bf16_f32 v148, v154, v155
	v_cvt_pk_bf16_f32 v149, v152, v153
	global_store_dwordx4 v[150:151], v[146:149], off
	v_pk_mul_f32 v[152:153], v[52:53], v[140:141] op_sel_hi:[1,0]
	v_pk_mul_f32 v[154:155], v[50:51], v[140:141] op_sel_hi:[1,0]
	v_pk_mul_f32 v[148:149], v[56:57], v[140:141] op_sel_hi:[1,0]
	v_pk_mul_f32 v[146:147], v[54:55], v[140:141] op_sel_hi:[1,0]
	v_add_u32_e32 v135, 0x90, v210
	v_cvt_pk_bf16_f32 v146, v146, v147
	v_cvt_pk_bf16_f32 v147, v148, v149
	v_cvt_pk_bf16_f32 v148, v154, v155
	v_cvt_pk_bf16_f32 v149, v152, v153
	global_store_dwordx4 v[150:151], v[146:149], off offset:256
	v_pk_mul_f32 v[152:153], v[44:45], v[138:139] op_sel_hi:[1,0]
	v_pk_mul_f32 v[154:155], v[42:43], v[138:139] op_sel_hi:[1,0]
	v_pk_mul_f32 v[148:149], v[48:49], v[138:139] op_sel_hi:[1,0]
	v_pk_mul_f32 v[146:147], v[46:47], v[138:139] op_sel_hi:[1,0]
	v_mad_i64_i32 v[150:151], s[8:9], v135, s69, v[144:145]
	v_cvt_pk_bf16_f32 v146, v146, v147
	v_cvt_pk_bf16_f32 v147, v148, v149
	v_cvt_pk_bf16_f32 v148, v154, v155
	v_cvt_pk_bf16_f32 v149, v152, v153
	global_store_dwordx4 v[150:151], v[146:149], off
	v_pk_mul_f32 v[152:153], v[36:37], v[138:139] op_sel_hi:[1,0]
	v_pk_mul_f32 v[154:155], v[34:35], v[138:139] op_sel_hi:[1,0]
	v_pk_mul_f32 v[148:149], v[40:41], v[138:139] op_sel_hi:[1,0]
	v_pk_mul_f32 v[146:147], v[38:39], v[138:139] op_sel_hi:[1,0]
	v_add_u32_e32 v135, 0xa0, v210
	v_cvt_pk_bf16_f32 v146, v146, v147
	v_cvt_pk_bf16_f32 v147, v148, v149
	v_cvt_pk_bf16_f32 v148, v154, v155
	v_cvt_pk_bf16_f32 v149, v152, v153
	global_store_dwordx4 v[150:151], v[146:149], off offset:256
	v_pk_mul_f32 v[152:153], v[28:29], v[134:135] op_sel_hi:[1,0]
	v_pk_mul_f32 v[154:155], v[26:27], v[134:135] op_sel_hi:[1,0]
	v_pk_mul_f32 v[148:149], v[32:33], v[134:135] op_sel_hi:[1,0]
	v_pk_mul_f32 v[146:147], v[30:31], v[134:135] op_sel_hi:[1,0]
	v_mad_i64_i32 v[150:151], s[8:9], v135, s69, v[144:145]
	v_cvt_pk_bf16_f32 v146, v146, v147
	v_cvt_pk_bf16_f32 v147, v148, v149
	v_cvt_pk_bf16_f32 v148, v154, v155
	v_cvt_pk_bf16_f32 v149, v152, v153
	global_store_dwordx4 v[150:151], v[146:149], off
	v_pk_mul_f32 v[152:153], v[20:21], v[134:135] op_sel_hi:[1,0]
	v_pk_mul_f32 v[154:155], v[18:19], v[134:135] op_sel_hi:[1,0]
	v_pk_mul_f32 v[148:149], v[24:25], v[134:135] op_sel_hi:[1,0]
	v_pk_mul_f32 v[146:147], v[22:23], v[134:135] op_sel_hi:[1,0]
	v_add_u32_e32 v135, 0xb0, v210
	v_cvt_pk_bf16_f32 v146, v146, v147
	v_cvt_pk_bf16_f32 v147, v148, v149
	v_cvt_pk_bf16_f32 v148, v154, v155
	v_cvt_pk_bf16_f32 v149, v152, v153
	global_store_dwordx4 v[150:151], v[146:149], off offset:256
	v_pk_mul_f32 v[150:151], v[12:13], v[136:137] op_sel_hi:[1,0]
	v_pk_mul_f32 v[152:153], v[10:11], v[136:137] op_sel_hi:[1,0]
	v_mad_i64_i32 v[148:149], s[8:9], v135, s69, v[144:145]
	v_pk_mul_f32 v[146:147], v[16:17], v[136:137] op_sel_hi:[1,0]
	v_pk_mul_f32 v[144:145], v[14:15], v[136:137] op_sel_hi:[1,0]
	s_mov_b64 s[8:9], 0
	v_cvt_pk_bf16_f32 v144, v144, v145
	v_cvt_pk_bf16_f32 v145, v146, v147
	v_cvt_pk_bf16_f32 v146, v152, v153
	v_cvt_pk_bf16_f32 v147, v150, v151
	global_store_dwordx4 v[148:149], v[144:147], off
	v_pk_mul_f32 v[150:151], v[4:5], v[136:137] op_sel_hi:[1,0]
	v_pk_mul_f32 v[152:153], v[2:3], v[136:137] op_sel_hi:[1,0]
	v_pk_mul_f32 v[146:147], v[8:9], v[136:137] op_sel_hi:[1,0]
	v_pk_mul_f32 v[144:145], v[6:7], v[136:137] op_sel_hi:[1,0]
	s_nop 0
	v_cvt_pk_bf16_f32 v144, v144, v145
	v_cvt_pk_bf16_f32 v145, v146, v147
	v_cvt_pk_bf16_f32 v146, v152, v153
	v_cvt_pk_bf16_f32 v147, v150, v151
	global_store_dwordx4 v[148:149], v[144:147], off offset:256
